# pass1 B/C staging loop: conv-tap row loads software-pipelined one iteration ahead into spare registers
# baseline (speedup 1.0000x reference)
.LBB0_931:
	s_or_b64 exec, exec, s[4:5]
	v_lshlrev_b32_e32 v1, 3, v40
	v_and_b32_e32 v19, 0x78, v1
	v_lshl_or_b32 v2, s14, 7, v19
	v_or_b32_e32 v20, 0x400, v2
	v_lshlrev_b32_e32 v10, 2, v20
	global_load_dwordx4 v[2:5], v10, s[22:23] offset:16
	global_load_dwordx4 v[6:9], v10, s[22:23]
	v_ashrrev_i32_e32 v18, 4, v40
	v_mov_b32_e32 v11, v0
	v_lshl_add_u64 v[10:11], s[20:21], 0, v[10:11]
	s_mov_b64 s[4:5], 0x1800
	v_mul_u32_u24_e32 v19, 0x110, v19
	v_lshlrev_b32_e32 v21, 1, v18
	s_add_u32 s40, s8, s10
	v_lshl_add_u64 v[12:13], v[10:11], 0, s[4:5]
	s_mov_b64 s[4:5], 0x3000
	v_add3_u32 v38, v19, v21, 0
	s_addc_u32 s41, s9, 0
	v_ashrrev_i32_e32 v19, 31, v18
	v_lshl_add_u64 v[14:15], v[10:11], 0, s[4:5]
	s_mov_b64 s[4:5], 0x4800
	v_add_u32_e32 v39, s10, v18
	v_lshl_add_u64 v[18:19], s[40:41], 0, v[18:19]
	v_lshlrev_b32_e32 v20, 1, v20
	v_mov_b32_e32 v21, v0
	v_lshl_add_u64 v[16:17], v[10:11], 0, s[4:5]
	v_mad_u64_u32 v[20:21], s[4:5], v18, s84, v[20:21]
	v_mad_i32_i24 v21, v19, s84, v21
	s_mov_b32 s7, s9
	v_lshl_add_u64 v[18:19], s[2:3], 0, v[20:21]
	s_mov_b64 s[4:5], 0
	global_load_dwordx4 v[50:53], v[10:11], off
	global_load_dwordx4 v[54:57], v[10:11], off offset:16
	global_load_dwordx4 v[58:61], v[12:13], off
	global_load_dwordx4 v[62:65], v[12:13], off offset:16
	global_load_dwordx4 v[66:69], v[14:15], off
	global_load_dwordx4 v[70:73], v[14:15], off offset:16
	global_load_dwordx4 v[74:77], v[16:17], off
	global_load_dwordx4 v[78:81], v[16:17], off offset:16
	v_lshrrev_b32_e32 v222, 6, v178
	v_and_b32_e32 v223, 7, v178
	v_bfe_u32 v224, v178, 3, 3
	v_lshlrev_b32_e32 v225, 6, v222
	v_lshl_add_u32 v225, v223, 3, v225
	v_mov_b32_e32 v226, s14
	v_lshl_add_u32 v225, v226, 9, v225
	v_lshrrev_b32_e32 v226, 1, v224
	v_mul_u32_u24_e32 v226, 0x600, v226
	v_add_u32_e32 v226, v226, v225
	v_and_b32_e32 v227, 1, v224
	v_lshlrev_b32_e32 v233, 2, v227
	v_add_lshl_u32 v226, v226, v233, 2
	global_load_dwordx4 v[228:231], v226, s[20:21]
	v_add_lshl_u32 v233, v225, v233, 2
	global_load_dwordx4 v[246:249], v233, s[22:23]
	v_mul_u32_u24_e32 v232, 0x500, v222
	v_lshl_add_u32 v232, v223, 4, v232
	v_add_u32_e32 v232, 0x24000, v232
	v_lshl_add_u32 v233, v227, 7, v232
	v_lshl_add_u32 v232, v224, 7, v232
	v_lshl_add_u64 v[22:23], v[18:19], 0, s[4:5]
	v_mov_b32_e32 v124, 0
	v_mov_b32_e32 v125, 0
	v_mov_b32_e32 v126, 0
	v_mov_b32_e32 v127, 0
	v_mov_b32_e32 v128, 0
	v_mov_b32_e32 v129, 0
	v_mov_b32_e32 v130, 0
	v_mov_b32_e32 v131, 0
	v_mov_b32_e32 v132, 0
	v_mov_b32_e32 v133, 0
	v_mov_b32_e32 v134, 0
	v_mov_b32_e32 v135, 0
	v_add_co_u32_e32 v42, vcc, 0x3201000, v22
	s_nop 1
	v_addc_co_u32_e32 v43, vcc, 0, v23, vcc
	global_load_dwordx4 v[136:139], v[42:43], off offset:2048
	v_cmp_lt_i32_e32 vcc, 0, v39
	s_and_saveexec_b64 s[8:9], vcc
	s_cbranch_execz .Lp1a_t2
	v_add_co_u32_e32 v42, vcc, 0x31ff000, v22
	s_nop 1
	v_addc_co_u32_e32 v43, vcc, 0, v23, vcc
	global_load_dwordx4 v[132:135], v[42:43], off offset:1024
.Lp1a_t2:
	s_or_b64 exec, exec, s[8:9]
	v_cmp_lt_i32_e32 vcc, 1, v39
	s_and_saveexec_b64 s[8:9], vcc
	s_cbranch_execz .Lp1a_t1
	v_add_co_u32_e32 v42, vcc, 0x31fd000, v22
	s_nop 1
	v_addc_co_u32_e32 v43, vcc, 0, v23, vcc
	global_load_dwordx4 v[128:131], v[42:43], off
.Lp1a_t1:
	s_or_b64 exec, exec, s[8:9]
	v_cmp_lt_i32_e32 vcc, 2, v39
	s_and_saveexec_b64 s[8:9], vcc
	s_cbranch_execz .Lp1a_t0
	v_add_co_u32_e32 v42, vcc, 0x31fa000, v22
	s_nop 1
	v_addc_co_u32_e32 v43, vcc, 0, v23, vcc
	global_load_dwordx4 v[124:127], v[42:43], off offset:3072
.Lp1a_t0:
	s_or_b64 exec, exec, s[8:9]
	s_branch .LBB0_933

.LBB0_933:
	s_waitcnt vmcnt(0)
	v_mov_b32_e32 v82, v124
	v_mov_b32_e32 v83, v125
	v_mov_b32_e32 v84, v126
	v_mov_b32_e32 v85, v127
	v_mov_b32_e32 v86, v128
	v_mov_b32_e32 v87, v129
	v_mov_b32_e32 v88, v130
	v_mov_b32_e32 v89, v131
	v_mov_b32_e32 v90, v132
	v_mov_b32_e32 v91, v133
	v_mov_b32_e32 v92, v134
	v_mov_b32_e32 v93, v135
	v_mov_b32_e32 v94, v136
	v_mov_b32_e32 v95, v137
	v_mov_b32_e32 v96, v138
	v_mov_b32_e32 v97, v139
	s_cmp_eq_u32 s4, 0xd8000
	s_cbranch_scc1 .Lp1n_skip
	v_lshl_add_u64 v[22:23], v[18:19], 0, s[4:5]
	v_mov_b32_e32 v124, 0
	v_mov_b32_e32 v125, 0
	v_mov_b32_e32 v126, 0
	v_mov_b32_e32 v127, 0
	v_mov_b32_e32 v128, 0
	v_mov_b32_e32 v129, 0
	v_mov_b32_e32 v130, 0
	v_mov_b32_e32 v131, 0
	v_mov_b32_e32 v132, 0
	v_mov_b32_e32 v133, 0
	v_mov_b32_e32 v134, 0
	v_mov_b32_e32 v135, 0
	v_add_co_u32_e32 v42, vcc, 0x3249000, v22
	s_nop 1
	v_addc_co_u32_e32 v43, vcc, 0, v23, vcc
	global_load_dwordx4 v[136:139], v[42:43], off offset:2048
	v_cmp_lt_i32_e32 vcc, 0xffffffe0, v39
	s_and_saveexec_b64 s[8:9], vcc
	s_cbranch_execz .Lp1n_t2
	v_add_co_u32_e32 v42, vcc, 0x3247000, v22
	s_nop 1
	v_addc_co_u32_e32 v43, vcc, 0, v23, vcc
	global_load_dwordx4 v[132:135], v[42:43], off offset:1024
.Lp1n_t2:
	s_or_b64 exec, exec, s[8:9]
	v_cmp_lt_i32_e32 vcc, 0xffffffe1, v39
	s_and_saveexec_b64 s[8:9], vcc
	s_cbranch_execz .Lp1n_t1
	v_add_co_u32_e32 v42, vcc, 0x3245000, v22
	s_nop 1
	v_addc_co_u32_e32 v43, vcc, 0, v23, vcc
	global_load_dwordx4 v[128:131], v[42:43], off
.Lp1n_t1:
	s_or_b64 exec, exec, s[8:9]
	v_cmp_lt_i32_e32 vcc, 0xffffffe2, v39
	s_and_saveexec_b64 s[8:9], vcc
	s_cbranch_execz .Lp1n_t0
	v_add_co_u32_e32 v42, vcc, 0x3242000, v22
	s_nop 1
	v_addc_co_u32_e32 v43, vcc, 0, v23, vcc
	global_load_dwordx4 v[124:127], v[42:43], off offset:3072

.Lp1n_skip:
	v_lshlrev_b32_e32 v42, 16, v82
	v_and_b32_e32 v43, 0xffff0000, v82
	v_pk_fma_f32 v[24:25], v[50:51], v[42:43], v[6:7]
	v_lshlrev_b32_e32 v44, 16, v83
	v_and_b32_e32 v45, 0xffff0000, v83
	v_pk_fma_f32 v[26:27], v[52:53], v[44:45], v[8:9]
	v_lshlrev_b32_e32 v42, 16, v84
	v_and_b32_e32 v43, 0xffff0000, v84
	v_pk_fma_f32 v[30:31], v[54:55], v[42:43], v[2:3]
	v_lshlrev_b32_e32 v44, 16, v85
	v_and_b32_e32 v45, 0xffff0000, v85
	v_pk_fma_f32 v[32:33], v[56:57], v[44:45], v[4:5]
	v_lshlrev_b32_e32 v42, 16, v86
	v_and_b32_e32 v43, 0xffff0000, v86
	v_pk_fma_f32 v[24:25], v[58:59], v[42:43], v[24:25]
	v_lshlrev_b32_e32 v44, 16, v87
	v_and_b32_e32 v45, 0xffff0000, v87
	v_pk_fma_f32 v[26:27], v[60:61], v[44:45], v[26:27]
	v_lshlrev_b32_e32 v42, 16, v88
	v_and_b32_e32 v43, 0xffff0000, v88
	v_pk_fma_f32 v[30:31], v[62:63], v[42:43], v[30:31]
	v_lshlrev_b32_e32 v44, 16, v89
	v_and_b32_e32 v45, 0xffff0000, v89
	v_pk_fma_f32 v[32:33], v[64:65], v[44:45], v[32:33]
	v_lshlrev_b32_e32 v42, 16, v90
	v_and_b32_e32 v43, 0xffff0000, v90
	v_pk_fma_f32 v[24:25], v[66:67], v[42:43], v[24:25]
	v_lshlrev_b32_e32 v44, 16, v91
	v_and_b32_e32 v45, 0xffff0000, v91
	v_pk_fma_f32 v[26:27], v[68:69], v[44:45], v[26:27]
	v_lshlrev_b32_e32 v42, 16, v92
	v_and_b32_e32 v43, 0xffff0000, v92
	v_pk_fma_f32 v[30:31], v[70:71], v[42:43], v[30:31]
	v_lshlrev_b32_e32 v44, 16, v93
	v_and_b32_e32 v45, 0xffff0000, v93
	v_pk_fma_f32 v[32:33], v[72:73], v[44:45], v[32:33]
	v_lshlrev_b32_e32 v42, 16, v94
	v_and_b32_e32 v43, 0xffff0000, v94
	v_pk_fma_f32 v[36:37], v[74:75], v[42:43], v[24:25]
	v_lshlrev_b32_e32 v44, 16, v95
	v_and_b32_e32 v45, 0xffff0000, v95
	v_pk_fma_f32 v[34:35], v[76:77], v[44:45], v[26:27]
	v_lshlrev_b32_e32 v42, 16, v96
	v_and_b32_e32 v43, 0xffff0000, v96
	v_pk_fma_f32 v[28:29], v[78:79], v[42:43], v[30:31]
	v_lshlrev_b32_e32 v44, 16, v97
	v_and_b32_e32 v45, 0xffff0000, v97
	v_pk_fma_f32 v[20:21], v[80:81], v[44:45], v[32:33]
	s_mov_b64 s[8:9], exec
	s_branch .LBB0_932
